# prologue mod_item k-loop unrolled x2 with the 16 row loads of each pair issued together
# baseline (speedup 1.0000x reference)
; __device__ __forceinline__ void mod_item(const Params& p, LAS unsigned char* lds, int item, int tid, int wave, int lane) {
;     ...
; #pragma unroll 1
;     for (int k8 = 0; k8 < 128; k8 += 8) {
;         f32x4 wv[8];
; #pragma unroll
;         for (int u = 0; u < 8; ++u) wv[u] = *(const f32x4*)(wp + (size_t)(k8 + u) * NMOD);
; #pragma unroll
;         for (int u = 0; u < 8; ++u)
; #pragma unroll
;             for (int r = 0; r < 9; ++r) { const float s = sv[r * 1024 + wave * 128 + k8 + u]; acc[r] += wv[u] * s; }
.LBB0_374:
	global_load_dwordx4 v[170:173], v[80:81], off
	v_add_co_u32_e32 v154, vcc, 0x6000, v80
	s_nop 1
	v_addc_co_u32_e32 v155, vcc, 0, v81, vcc
	global_load_dwordx4 v[174:177], v[154:155], off
	v_add_co_u32_e32 v154, vcc, 0x6000, v154
	s_nop 1
	v_addc_co_u32_e32 v155, vcc, 0, v155, vcc
	global_load_dwordx4 v[178:181], v[154:155], off
	v_add_co_u32_e32 v154, vcc, 0x6000, v154
	s_nop 1
	v_addc_co_u32_e32 v155, vcc, 0, v155, vcc
	global_load_dwordx4 v[182:185], v[154:155], off
	v_add_co_u32_e32 v154, vcc, 0x6000, v154
	s_nop 1
	v_addc_co_u32_e32 v155, vcc, 0, v155, vcc
	global_load_dwordx4 v[186:189], v[154:155], off
	v_add_co_u32_e32 v154, vcc, 0x6000, v154
	s_nop 1
	v_addc_co_u32_e32 v155, vcc, 0, v155, vcc
	global_load_dwordx4 v[190:193], v[154:155], off
	v_add_co_u32_e32 v154, vcc, 0x6000, v154
	s_nop 1
	v_addc_co_u32_e32 v155, vcc, 0, v155, vcc
	global_load_dwordx4 v[194:197], v[154:155], off
	v_add_co_u32_e32 v154, vcc, 0x6000, v154
	s_nop 1
	v_addc_co_u32_e32 v155, vcc, 0, v155, vcc
	global_load_dwordx4 v[198:201], v[154:155], off
	v_add_co_u32_e32 v154, vcc, 0x6000, v154
	s_nop 1
	v_addc_co_u32_e32 v155, vcc, 0, v155, vcc
	global_load_dwordx4 v[202:205], v[154:155], off
	v_add_co_u32_e32 v154, vcc, 0x6000, v154
	s_nop 1
	v_addc_co_u32_e32 v155, vcc, 0, v155, vcc
	global_load_dwordx4 v[206:209], v[154:155], off
	v_add_co_u32_e32 v154, vcc, 0x6000, v154
	s_nop 1
	v_addc_co_u32_e32 v155, vcc, 0, v155, vcc
	global_load_dwordx4 v[210:213], v[154:155], off
	v_add_co_u32_e32 v154, vcc, 0x6000, v154
	s_nop 1
	v_addc_co_u32_e32 v155, vcc, 0, v155, vcc
	global_load_dwordx4 v[214:217], v[154:155], off
	v_add_co_u32_e32 v154, vcc, 0x6000, v154
	s_nop 1
	v_addc_co_u32_e32 v155, vcc, 0, v155, vcc
	global_load_dwordx4 v[224:227], v[154:155], off
	v_add_co_u32_e32 v154, vcc, 0x6000, v154
	s_nop 1
	v_addc_co_u32_e32 v155, vcc, 0, v155, vcc
	global_load_dwordx4 v[228:231], v[154:155], off
	v_add_co_u32_e32 v154, vcc, 0x6000, v154
	s_nop 1
	v_addc_co_u32_e32 v155, vcc, 0, v155, vcc
	global_load_dwordx4 v[232:235], v[154:155], off
	v_add_co_u32_e32 v154, vcc, 0x6000, v154
	s_nop 1
	v_addc_co_u32_e32 v155, vcc, 0, v155, vcc
	global_load_dwordx4 v[236:239], v[154:155], off
	v_mov_b32_e32 v122, s12
	ds_read_b128 v[8:11], v122
	ds_read_b128 v[16:19], v122 offset:16
	ds_read_b128 v[40:43], v122 offset:4096
	ds_read_b128 v[44:47], v122 offset:8192
	ds_read_b128 v[20:23], v122 offset:4112
	ds_read_b128 v[24:27], v122 offset:8208
	s_movk_i32 s13, 0x6000
	s_add_i32 s11, s11, 8
	s_add_i32 s12, s12, 32
	s_mov_b64 s[14:15], 0x30000
	s_cmpk_gt_u32 s11, 0x77
	s_waitcnt vmcnt(15) lgkmcnt(2)
	v_mov_b32_e32 v118, v170
	v_mov_b32_e32 v119, v171
	v_mov_b32_e32 v120, v172
	v_mov_b32_e32 v121, v173
	v_pk_fma_f32 v[90:91], v[120:121], v[44:45], v[30:31] op_sel_hi:[1,0,1]
	v_pk_fma_f32 v[92:93], v[118:119], v[44:45], v[28:29] op_sel_hi:[1,0,1]
	ds_read_b128 v[48:51], v122 offset:12288
	ds_read_b128 v[28:31], v122 offset:12304
	v_pk_fma_f32 v[86:87], v[120:121], v[40:41], v[6:7] op_sel_hi:[1,0,1]
	v_pk_fma_f32 v[88:89], v[118:119], v[40:41], v[4:5] op_sel_hi:[1,0,1]
	v_pk_fma_f32 v[82:83], v[120:121], v[8:9], v[2:3] op_sel_hi:[1,0,1]
	s_waitcnt lgkmcnt(1)
	v_pk_fma_f32 v[94:95], v[120:121], v[48:49], v[34:35] op_sel_hi:[1,0,1]
	v_pk_fma_f32 v[96:97], v[118:119], v[48:49], v[32:33] op_sel_hi:[1,0,1]
	ds_read_b128 v[52:55], v122 offset:16384
	ds_read_b128 v[32:35], v122 offset:16400
	v_pk_fma_f32 v[84:85], v[118:119], v[8:9], v[0:1] op_sel_hi:[1,0,1]
	s_waitcnt lgkmcnt(1)
	v_pk_fma_f32 v[98:99], v[120:121], v[52:53], v[38:39] op_sel_hi:[1,0,1]
	v_pk_fma_f32 v[100:101], v[118:119], v[52:53], v[36:37] op_sel_hi:[1,0,1]
	ds_read_b128 v[56:59], v122 offset:20480
	ds_read_b128 v[36:39], v122 offset:20496
	s_waitcnt lgkmcnt(1)
	v_pk_fma_f32 v[102:103], v[120:121], v[56:57], v[62:63] op_sel_hi:[1,0,1]
	v_pk_fma_f32 v[104:105], v[118:119], v[56:57], v[60:61] op_sel_hi:[1,0,1]
	ds_read_b128 v[60:63], v122 offset:24576
	ds_read_b128 v[12:15], v122 offset:24592
	s_waitcnt lgkmcnt(1)
	v_pk_fma_f32 v[106:107], v[120:121], v[60:61], v[66:67] op_sel_hi:[1,0,1]
	v_pk_fma_f32 v[108:109], v[118:119], v[60:61], v[64:65] op_sel_hi:[1,0,1]
	ds_read_b128 v[64:67], v122 offset:28672
	ds_read_b128 v[4:7], v122 offset:28688
	s_waitcnt lgkmcnt(1)
	v_pk_fma_f32 v[110:111], v[120:121], v[64:65], v[70:71] op_sel_hi:[1,0,1]
	v_pk_fma_f32 v[112:113], v[118:119], v[64:65], v[68:69] op_sel_hi:[1,0,1]
	ds_read_b128 v[68:71], v122 offset:32768
	ds_read_b128 v[0:3], v122 offset:32784
	s_waitcnt lgkmcnt(1)
	v_pk_fma_f32 v[72:73], v[118:119], v[68:69], v[72:73] op_sel_hi:[1,0,1]
	v_add_co_u32_e32 v118, vcc, s13, v80
	s_mov_b32 s13, 0xc000
	s_nop 0
	v_addc_co_u32_e32 v119, vcc, 0, v81, vcc
	v_add_co_u32_e32 v122, vcc, s13, v80
	v_pk_fma_f32 v[74:75], v[120:121], v[68:69], v[74:75] op_sel_hi:[1,0,1]
	s_nop 0
	v_addc_co_u32_e32 v123, vcc, 0, v81, vcc
	s_nop 0
	s_nop 0
	s_nop 0
	s_mov_b32 s13, 0x12000
	s_waitcnt vmcnt(14)
	v_mov_b32_e32 v118, v174
	v_mov_b32_e32 v119, v175
	v_mov_b32_e32 v120, v176
	v_mov_b32_e32 v121, v177
	v_pk_fma_f32 v[82:83], v[120:121], v[8:9], v[82:83] op_sel:[0,1,0]
	v_pk_fma_f32 v[8:9], v[118:119], v[8:9], v[84:85] op_sel:[0,1,0]
	v_pk_fma_f32 v[74:75], v[120:121], v[68:69], v[74:75] op_sel:[0,1,0]
	v_pk_fma_f32 v[68:69], v[118:119], v[68:69], v[72:73] op_sel:[0,1,0]
	s_waitcnt vmcnt(13)
; __device__ __forceinline__ void mod_item(const Params& p, LAS unsigned char* lds, int item, int tid, int wave, int lane) {
;     ...
;         for (int u = 0; u < 8; ++u) wv[u] = *(const f32x4*)(wp + (size_t)(k8 + u) * NMOD);
; #pragma unroll
;         for (int u = 0; u < 8; ++u)
; #pragma unroll
;             for (int r = 0; r < 9; ++r) { const float s = sv[r * 1024 + wave * 128 + k8 + u]; acc[r] += wv[u] * s; }
	v_mov_b32_e32 v122, v178
	v_mov_b32_e32 v123, v179
	v_mov_b32_e32 v124, v180
	v_mov_b32_e32 v125, v181
	v_pk_fma_f32 v[72:73], v[124:125], v[10:11], v[82:83] op_sel_hi:[1,0,1]
	v_pk_fma_f32 v[82:83], v[122:123], v[10:11], v[8:9] op_sel_hi:[1,0,1]
	v_add_co_u32_e32 v8, vcc, s13, v80
	v_pk_fma_f32 v[84:85], v[120:121], v[40:41], v[86:87] op_sel:[0,1,0]
	v_pk_fma_f32 v[40:41], v[118:119], v[40:41], v[88:89] op_sel:[0,1,0]
	v_addc_co_u32_e32 v9, vcc, 0, v81, vcc
	s_mov_b32 s13, 0x18000
	v_pk_fma_f32 v[86:87], v[120:121], v[44:45], v[90:91] op_sel:[0,1,0]
	v_pk_fma_f32 v[90:91], v[120:121], v[52:53], v[98:99] op_sel:[0,1,0]
	v_pk_fma_f32 v[98:99], v[122:123], v[42:43], v[40:41] op_sel_hi:[1,0,1]
	v_add_co_u32_e32 v40, vcc, s13, v80
	v_pk_fma_f32 v[44:45], v[118:119], v[44:45], v[92:93] op_sel:[0,1,0]
	v_pk_fma_f32 v[88:89], v[120:121], v[48:49], v[94:95] op_sel:[0,1,0]
	v_pk_fma_f32 v[48:49], v[118:119], v[48:49], v[96:97] op_sel:[0,1,0]
	v_addc_co_u32_e32 v41, vcc, 0, v81, vcc
	v_pk_fma_f32 v[84:85], v[124:125], v[42:43], v[84:85] op_sel_hi:[1,0,1]
	v_pk_fma_f32 v[86:87], v[124:125], v[46:47], v[86:87] op_sel_hi:[1,0,1]
	v_pk_fma_f32 v[44:45], v[122:123], v[46:47], v[44:45] op_sel_hi:[1,0,1]
	v_pk_fma_f32 v[88:89], v[124:125], v[50:51], v[88:89] op_sel_hi:[1,0,1]
	v_pk_fma_f32 v[48:49], v[122:123], v[50:51], v[48:49] op_sel_hi:[1,0,1]
	v_mov_b32_e32 v46, v11
	v_mov_b32_e32 v50, v43
	s_nop 0
	s_nop 0
	s_nop 0
	v_pk_fma_f32 v[52:53], v[118:119], v[52:53], v[100:101] op_sel:[0,1,0]
	v_pk_fma_f32 v[92:93], v[120:121], v[56:57], v[102:103] op_sel:[0,1,0]
	v_pk_fma_f32 v[56:57], v[118:119], v[56:57], v[104:105] op_sel:[0,1,0]
	v_pk_fma_f32 v[94:95], v[120:121], v[60:61], v[106:107] op_sel:[0,1,0]
	v_pk_fma_f32 v[60:61], v[118:119], v[60:61], v[108:109] op_sel:[0,1,0]
	v_pk_fma_f32 v[96:97], v[120:121], v[64:65], v[110:111] op_sel:[0,1,0]
	v_pk_fma_f32 v[64:65], v[118:119], v[64:65], v[112:113] op_sel:[0,1,0]
	v_pk_fma_f32 v[90:91], v[124:125], v[54:55], v[90:91] op_sel_hi:[1,0,1]
	v_pk_fma_f32 v[52:53], v[122:123], v[54:55], v[52:53] op_sel_hi:[1,0,1]
	v_pk_fma_f32 v[92:93], v[124:125], v[58:59], v[92:93] op_sel_hi:[1,0,1]
	v_pk_fma_f32 v[56:57], v[122:123], v[58:59], v[56:57] op_sel_hi:[1,0,1]
	v_pk_fma_f32 v[94:95], v[124:125], v[62:63], v[94:95] op_sel_hi:[1,0,1]
	v_pk_fma_f32 v[60:61], v[122:123], v[62:63], v[60:61] op_sel_hi:[1,0,1]
	v_pk_fma_f32 v[96:97], v[124:125], v[66:67], v[96:97] op_sel_hi:[1,0,1]
	v_pk_fma_f32 v[64:65], v[122:123], v[66:67], v[64:65] op_sel_hi:[1,0,1]
	v_pk_fma_f32 v[74:75], v[124:125], v[70:71], v[74:75] op_sel_hi:[1,0,1]
	v_pk_fma_f32 v[68:69], v[122:123], v[70:71], v[68:69] op_sel_hi:[1,0,1]
	v_mov_b32_e32 v54, v47
	v_mov_b32_e32 v58, v51
	v_mov_b32_e32 v62, v55
	v_mov_b32_e32 v66, v59
	v_mov_b32_e32 v70, v63
	v_mov_b32_e32 v100, v67
	v_mov_b32_e32 v102, v71
	s_mov_b32 s13, 0x1e000
	s_waitcnt vmcnt(12)
	v_mov_b32_e32 v8, v182
	v_mov_b32_e32 v9, v183
	v_mov_b32_e32 v10, v184
	v_mov_b32_e32 v11, v185
	v_pk_fma_f32 v[72:73], v[10:11], v[46:47], v[72:73] op_sel_hi:[1,0,1]
	v_pk_fma_f32 v[46:47], v[8:9], v[46:47], v[82:83] op_sel_hi:[1,0,1]
	v_pk_fma_f32 v[82:83], v[10:11], v[50:51], v[84:85] op_sel_hi:[1,0,1]
	v_pk_fma_f32 v[50:51], v[8:9], v[50:51], v[98:99] op_sel_hi:[1,0,1]
	v_pk_fma_f32 v[84:85], v[10:11], v[54:55], v[86:87] op_sel_hi:[1,0,1]
	v_pk_fma_f32 v[44:45], v[8:9], v[54:55], v[44:45] op_sel_hi:[1,0,1]
	v_pk_fma_f32 v[48:49], v[8:9], v[58:59], v[48:49] op_sel_hi:[1,0,1]
	v_pk_fma_f32 v[52:53], v[8:9], v[62:63], v[52:53] op_sel_hi:[1,0,1]
	v_pk_fma_f32 v[56:57], v[8:9], v[66:67], v[56:57] op_sel_hi:[1,0,1]
	v_pk_fma_f32 v[60:61], v[8:9], v[70:71], v[60:61] op_sel_hi:[1,0,1]
	v_pk_fma_f32 v[64:65], v[8:9], v[100:101], v[64:65] op_sel_hi:[1,0,1]
	v_pk_fma_f32 v[8:9], v[8:9], v[102:103], v[68:69] op_sel_hi:[1,0,1]
	v_pk_fma_f32 v[54:55], v[10:11], v[58:59], v[88:89] op_sel_hi:[1,0,1]
	v_pk_fma_f32 v[58:59], v[10:11], v[62:63], v[90:91] op_sel_hi:[1,0,1]
	v_pk_fma_f32 v[62:63], v[10:11], v[66:67], v[92:93] op_sel_hi:[1,0,1]
	v_pk_fma_f32 v[66:67], v[10:11], v[70:71], v[94:95] op_sel_hi:[1,0,1]
	v_pk_fma_f32 v[70:71], v[10:11], v[100:101], v[96:97] op_sel_hi:[1,0,1]
	v_pk_fma_f32 v[10:11], v[10:11], v[102:103], v[74:75] op_sel_hi:[1,0,1]
	s_waitcnt vmcnt(11)
	v_mov_b32_e32 v40, v186
	v_mov_b32_e32 v41, v187
	v_mov_b32_e32 v42, v188
	v_mov_b32_e32 v43, v189
	v_pk_fma_f32 v[74:75], v[42:43], v[24:25], v[84:85] op_sel_hi:[1,0,1]
	s_waitcnt lgkmcnt(0)
	v_pk_fma_f32 v[84:85], v[40:41], v[0:1], v[8:9] op_sel_hi:[1,0,1]
	v_add_co_u32_e32 v8, vcc, s13, v80
	s_mov_b32 s13, 0x24000
	s_nop 0
	v_addc_co_u32_e32 v9, vcc, 0, v81, vcc
	v_pk_fma_f32 v[68:69], v[42:43], v[16:17], v[72:73] op_sel_hi:[1,0,1]
	v_pk_fma_f32 v[72:73], v[42:43], v[20:21], v[82:83] op_sel_hi:[1,0,1]
	v_pk_fma_f32 v[82:83], v[42:43], v[0:1], v[10:11] op_sel_hi:[1,0,1]
	v_add_co_u32_e32 v10, vcc, s13, v80
	v_pk_fma_f32 v[46:47], v[40:41], v[16:17], v[46:47] op_sel_hi:[1,0,1]
	s_nop 0
	v_addc_co_u32_e32 v11, vcc, 0, v81, vcc
	v_pk_fma_f32 v[50:51], v[40:41], v[20:21], v[50:51] op_sel_hi:[1,0,1]
	v_pk_fma_f32 v[44:45], v[40:41], v[24:25], v[44:45] op_sel_hi:[1,0,1]
	v_pk_fma_f32 v[54:55], v[42:43], v[28:29], v[54:55] op_sel_hi:[1,0,1]
	v_pk_fma_f32 v[48:49], v[40:41], v[28:29], v[48:49] op_sel_hi:[1,0,1]
	v_pk_fma_f32 v[58:59], v[42:43], v[32:33], v[58:59] op_sel_hi:[1,0,1]
	v_pk_fma_f32 v[52:53], v[40:41], v[32:33], v[52:53] op_sel_hi:[1,0,1]
	v_pk_fma_f32 v[62:63], v[42:43], v[36:37], v[62:63] op_sel_hi:[1,0,1]
	v_pk_fma_f32 v[56:57], v[40:41], v[36:37], v[56:57] op_sel_hi:[1,0,1]
	v_pk_fma_f32 v[66:67], v[42:43], v[12:13], v[66:67] op_sel_hi:[1,0,1]
	v_pk_fma_f32 v[60:61], v[40:41], v[12:13], v[60:61] op_sel_hi:[1,0,1]
	v_pk_fma_f32 v[70:71], v[42:43], v[4:5], v[70:71] op_sel_hi:[1,0,1]
	v_pk_fma_f32 v[64:65], v[40:41], v[4:5], v[64:65] op_sel_hi:[1,0,1]
	s_nop 0
	s_nop 0
	s_nop 0
	s_mov_b32 s13, 0x2a000
	s_waitcnt vmcnt(10)
; __device__ __forceinline__ void mod_item(const Params& p, LAS unsigned char* lds, int item, int tid, int wave, int lane) {
;     ...
;         for (int u = 0; u < 8; ++u) wv[u] = *(const f32x4*)(wp + (size_t)(k8 + u) * NMOD);
; #pragma unroll
;         for (int u = 0; u < 8; ++u)
; #pragma unroll
;             for (int r = 0; r < 9; ++r) { const float s = sv[r * 1024 + wave * 128 + k8 + u]; acc[r] += wv[u] * s; }
	v_mov_b32_e32 v40, v190
	v_mov_b32_e32 v41, v191
	v_mov_b32_e32 v42, v192
	v_mov_b32_e32 v43, v193
	v_pk_fma_f32 v[68:69], v[42:43], v[16:17], v[68:69] op_sel:[0,1,0]
	v_pk_fma_f32 v[46:47], v[40:41], v[16:17], v[46:47] op_sel:[0,1,0]
	v_pk_fma_f32 v[72:73], v[42:43], v[20:21], v[72:73] op_sel:[0,1,0]
	v_pk_fma_f32 v[50:51], v[40:41], v[20:21], v[50:51] op_sel:[0,1,0]
	v_pk_fma_f32 v[74:75], v[42:43], v[24:25], v[74:75] op_sel:[0,1,0]
	v_pk_fma_f32 v[44:45], v[40:41], v[24:25], v[44:45] op_sel:[0,1,0]
	v_pk_fma_f32 v[54:55], v[42:43], v[28:29], v[54:55] op_sel:[0,1,0]
	v_pk_fma_f32 v[48:49], v[40:41], v[28:29], v[48:49] op_sel:[0,1,0]
	v_pk_fma_f32 v[58:59], v[42:43], v[32:33], v[58:59] op_sel:[0,1,0]
	v_pk_fma_f32 v[52:53], v[40:41], v[32:33], v[52:53] op_sel:[0,1,0]
	v_pk_fma_f32 v[86:87], v[42:43], v[36:37], v[62:63] op_sel:[0,1,0]
	v_pk_fma_f32 v[56:57], v[40:41], v[36:37], v[56:57] op_sel:[0,1,0]
	v_pk_fma_f32 v[66:67], v[42:43], v[12:13], v[66:67] op_sel:[0,1,0]
	v_pk_fma_f32 v[12:13], v[40:41], v[12:13], v[60:61] op_sel:[0,1,0]
	v_pk_fma_f32 v[60:61], v[42:43], v[4:5], v[70:71] op_sel:[0,1,0]
	v_pk_fma_f32 v[62:63], v[40:41], v[4:5], v[64:65] op_sel:[0,1,0]
	v_pk_fma_f32 v[4:5], v[42:43], v[0:1], v[82:83] op_sel:[0,1,0]
	v_pk_fma_f32 v[0:1], v[40:41], v[0:1], v[84:85] op_sel:[0,1,0]
	s_waitcnt vmcnt(9)
	v_mov_b32_e32 v8, v194
	v_mov_b32_e32 v9, v195
	v_mov_b32_e32 v10, v196
	v_mov_b32_e32 v11, v197
	v_pk_fma_f32 v[16:17], v[10:11], v[18:19], v[68:69] op_sel_hi:[1,0,1]
	v_pk_fma_f32 v[20:21], v[8:9], v[18:19], v[46:47] op_sel_hi:[1,0,1]
	v_mov_b32_e32 v28, v19
	v_pk_fma_f32 v[18:19], v[10:11], v[22:23], v[72:73] op_sel_hi:[1,0,1]
	v_pk_fma_f32 v[24:25], v[8:9], v[22:23], v[50:51] op_sel_hi:[1,0,1]
	v_mov_b32_e32 v36, v23
	v_pk_fma_f32 v[22:23], v[10:11], v[26:27], v[74:75] op_sel_hi:[1,0,1]
	v_pk_fma_f32 v[32:33], v[8:9], v[26:27], v[44:45] op_sel_hi:[1,0,1]
	v_mov_b32_e32 v42, v27
	v_pk_fma_f32 v[26:27], v[10:11], v[30:31], v[54:55] op_sel_hi:[1,0,1]
	v_pk_fma_f32 v[40:41], v[8:9], v[30:31], v[48:49] op_sel_hi:[1,0,1]
	v_add_co_u32_e32 v30, vcc, s13, v80
	v_mov_b32_e32 v48, v31
	s_nop 0
	v_addc_co_u32_e32 v31, vcc, 0, v81, vcc
	v_pk_fma_f32 v[44:45], v[10:11], v[34:35], v[58:59] op_sel_hi:[1,0,1]
	v_pk_fma_f32 v[58:59], v[10:11], v[14:15], v[66:67] op_sel_hi:[1,0,1]
	v_pk_fma_f32 v[64:65], v[8:9], v[14:15], v[12:13] op_sel_hi:[1,0,1]
	v_mov_b32_e32 v68, v15
	s_nop 0
	v_pk_fma_f32 v[46:47], v[8:9], v[34:35], v[52:53] op_sel_hi:[1,0,1]
	v_mov_b32_e32 v54, v35
	v_pk_fma_f32 v[50:51], v[10:11], v[38:39], v[86:87] op_sel_hi:[1,0,1]
	v_pk_fma_f32 v[52:53], v[8:9], v[38:39], v[56:57] op_sel_hi:[1,0,1]
	v_mov_b32_e32 v56, v39
	v_pk_fma_f32 v[70:71], v[10:11], v[6:7], v[60:61] op_sel_hi:[1,0,1]
	v_pk_fma_f32 v[72:73], v[8:9], v[6:7], v[62:63] op_sel_hi:[1,0,1]
	v_mov_b32_e32 v74, v7
	v_mov_b32_e32 v82, v3
	v_pk_fma_f32 v[10:11], v[10:11], v[2:3], v[4:5] op_sel_hi:[1,0,1]
	v_pk_fma_f32 v[8:9], v[8:9], v[2:3], v[0:1] op_sel_hi:[1,0,1]
	v_lshl_add_u64 v[80:81], v[80:81], 0, s[14:15]
	s_waitcnt vmcnt(8)
	v_mov_b32_e32 v12, v198
	v_mov_b32_e32 v13, v199
	v_mov_b32_e32 v14, v200
	v_mov_b32_e32 v15, v201
	v_pk_fma_f32 v[2:3], v[14:15], v[28:29], v[16:17] op_sel_hi:[1,0,1]
	v_pk_fma_f32 v[0:1], v[12:13], v[28:29], v[20:21] op_sel_hi:[1,0,1]
	v_pk_fma_f32 v[6:7], v[14:15], v[36:37], v[18:19] op_sel_hi:[1,0,1]
	v_pk_fma_f32 v[4:5], v[12:13], v[36:37], v[24:25] op_sel_hi:[1,0,1]
	v_pk_fma_f32 v[30:31], v[14:15], v[42:43], v[22:23] op_sel_hi:[1,0,1]
	v_pk_fma_f32 v[28:29], v[12:13], v[42:43], v[32:33] op_sel_hi:[1,0,1]
	v_pk_fma_f32 v[34:35], v[14:15], v[48:49], v[26:27] op_sel_hi:[1,0,1]
	v_pk_fma_f32 v[32:33], v[12:13], v[48:49], v[40:41] op_sel_hi:[1,0,1]
	v_pk_fma_f32 v[38:39], v[14:15], v[54:55], v[44:45] op_sel_hi:[1,0,1]
	v_pk_fma_f32 v[36:37], v[12:13], v[54:55], v[46:47] op_sel_hi:[1,0,1]
	v_pk_fma_f32 v[62:63], v[14:15], v[56:57], v[50:51] op_sel_hi:[1,0,1]
	v_pk_fma_f32 v[60:61], v[12:13], v[56:57], v[52:53] op_sel_hi:[1,0,1]
	v_pk_fma_f32 v[66:67], v[14:15], v[68:69], v[58:59] op_sel_hi:[1,0,1]
	v_pk_fma_f32 v[64:65], v[12:13], v[68:69], v[64:65] op_sel_hi:[1,0,1]
	v_pk_fma_f32 v[70:71], v[14:15], v[74:75], v[70:71] op_sel_hi:[1,0,1]
	v_pk_fma_f32 v[68:69], v[12:13], v[74:75], v[72:73] op_sel_hi:[1,0,1]
	v_pk_fma_f32 v[74:75], v[14:15], v[82:83], v[10:11] op_sel_hi:[1,0,1]
	v_pk_fma_f32 v[72:73], v[12:13], v[82:83], v[8:9] op_sel_hi:[1,0,1]
	s_nop 0
	v_mov_b32_e32 v122, s12
	ds_read_b128 v[8:11], v122
	ds_read_b128 v[16:19], v122 offset:16
	ds_read_b128 v[40:43], v122 offset:4096
	ds_read_b128 v[44:47], v122 offset:8192
	ds_read_b128 v[20:23], v122 offset:4112
	ds_read_b128 v[24:27], v122 offset:8208
	s_movk_i32 s13, 0x6000
	s_add_i32 s11, s11, 8
	s_add_i32 s12, s12, 32
	s_mov_b64 s[14:15], 0x30000
	s_cmpk_gt_u32 s11, 0x77
	s_waitcnt vmcnt(7) lgkmcnt(2)
	v_mov_b32_e32 v118, v202
	v_mov_b32_e32 v119, v203
	v_mov_b32_e32 v120, v204
	v_mov_b32_e32 v121, v205
	v_pk_fma_f32 v[90:91], v[120:121], v[44:45], v[30:31] op_sel_hi:[1,0,1]
	v_pk_fma_f32 v[92:93], v[118:119], v[44:45], v[28:29] op_sel_hi:[1,0,1]
	ds_read_b128 v[48:51], v122 offset:12288
	ds_read_b128 v[28:31], v122 offset:12304
	v_pk_fma_f32 v[86:87], v[120:121], v[40:41], v[6:7] op_sel_hi:[1,0,1]
	v_pk_fma_f32 v[88:89], v[118:119], v[40:41], v[4:5] op_sel_hi:[1,0,1]
	v_pk_fma_f32 v[82:83], v[120:121], v[8:9], v[2:3] op_sel_hi:[1,0,1]
	s_waitcnt lgkmcnt(1)
	v_pk_fma_f32 v[94:95], v[120:121], v[48:49], v[34:35] op_sel_hi:[1,0,1]
	v_pk_fma_f32 v[96:97], v[118:119], v[48:49], v[32:33] op_sel_hi:[1,0,1]
	ds_read_b128 v[52:55], v122 offset:16384
	ds_read_b128 v[32:35], v122 offset:16400
	v_pk_fma_f32 v[84:85], v[118:119], v[8:9], v[0:1] op_sel_hi:[1,0,1]
	s_waitcnt lgkmcnt(1)
; __device__ __forceinline__ void mod_item(const Params& p, LAS unsigned char* lds, int item, int tid, int wave, int lane) {
;     ...
;         for (int u = 0; u < 8; ++u) wv[u] = *(const f32x4*)(wp + (size_t)(k8 + u) * NMOD);
; #pragma unroll
;         for (int u = 0; u < 8; ++u)
; #pragma unroll
;             for (int r = 0; r < 9; ++r) { const float s = sv[r * 1024 + wave * 128 + k8 + u]; acc[r] += wv[u] * s; }
	v_pk_fma_f32 v[98:99], v[120:121], v[52:53], v[38:39] op_sel_hi:[1,0,1]
	v_pk_fma_f32 v[100:101], v[118:119], v[52:53], v[36:37] op_sel_hi:[1,0,1]
	ds_read_b128 v[56:59], v122 offset:20480
	ds_read_b128 v[36:39], v122 offset:20496
	s_waitcnt lgkmcnt(1)
	v_pk_fma_f32 v[102:103], v[120:121], v[56:57], v[62:63] op_sel_hi:[1,0,1]
	v_pk_fma_f32 v[104:105], v[118:119], v[56:57], v[60:61] op_sel_hi:[1,0,1]
	ds_read_b128 v[60:63], v122 offset:24576
	ds_read_b128 v[12:15], v122 offset:24592
	s_waitcnt lgkmcnt(1)
	v_pk_fma_f32 v[106:107], v[120:121], v[60:61], v[66:67] op_sel_hi:[1,0,1]
	v_pk_fma_f32 v[108:109], v[118:119], v[60:61], v[64:65] op_sel_hi:[1,0,1]
	ds_read_b128 v[64:67], v122 offset:28672
	ds_read_b128 v[4:7], v122 offset:28688
	s_waitcnt lgkmcnt(1)
	v_pk_fma_f32 v[110:111], v[120:121], v[64:65], v[70:71] op_sel_hi:[1,0,1]
	v_pk_fma_f32 v[112:113], v[118:119], v[64:65], v[68:69] op_sel_hi:[1,0,1]
	ds_read_b128 v[68:71], v122 offset:32768
	ds_read_b128 v[0:3], v122 offset:32784
	s_waitcnt lgkmcnt(1)
	v_pk_fma_f32 v[72:73], v[118:119], v[68:69], v[72:73] op_sel_hi:[1,0,1]
	v_add_co_u32_e32 v118, vcc, s13, v80
	s_mov_b32 s13, 0xc000
	s_nop 0
	v_addc_co_u32_e32 v119, vcc, 0, v81, vcc
	v_add_co_u32_e32 v122, vcc, s13, v80
	v_pk_fma_f32 v[74:75], v[120:121], v[68:69], v[74:75] op_sel_hi:[1,0,1]
	s_nop 0
	v_addc_co_u32_e32 v123, vcc, 0, v81, vcc
	s_nop 0
	s_nop 0
	s_nop 0
	s_mov_b32 s13, 0x12000
	s_waitcnt vmcnt(6)
	v_mov_b32_e32 v118, v206
	v_mov_b32_e32 v119, v207
	v_mov_b32_e32 v120, v208
	v_mov_b32_e32 v121, v209
	v_pk_fma_f32 v[82:83], v[120:121], v[8:9], v[82:83] op_sel:[0,1,0]
	v_pk_fma_f32 v[8:9], v[118:119], v[8:9], v[84:85] op_sel:[0,1,0]
	v_pk_fma_f32 v[74:75], v[120:121], v[68:69], v[74:75] op_sel:[0,1,0]
	v_pk_fma_f32 v[68:69], v[118:119], v[68:69], v[72:73] op_sel:[0,1,0]
	s_waitcnt vmcnt(5)
	v_mov_b32_e32 v122, v210
	v_mov_b32_e32 v123, v211
	v_mov_b32_e32 v124, v212
	v_mov_b32_e32 v125, v213
	v_pk_fma_f32 v[72:73], v[124:125], v[10:11], v[82:83] op_sel_hi:[1,0,1]
	v_pk_fma_f32 v[82:83], v[122:123], v[10:11], v[8:9] op_sel_hi:[1,0,1]
	v_add_co_u32_e32 v8, vcc, s13, v80
	v_pk_fma_f32 v[84:85], v[120:121], v[40:41], v[86:87] op_sel:[0,1,0]
	v_pk_fma_f32 v[40:41], v[118:119], v[40:41], v[88:89] op_sel:[0,1,0]
	v_addc_co_u32_e32 v9, vcc, 0, v81, vcc
	s_mov_b32 s13, 0x18000
	v_pk_fma_f32 v[86:87], v[120:121], v[44:45], v[90:91] op_sel:[0,1,0]
	v_pk_fma_f32 v[90:91], v[120:121], v[52:53], v[98:99] op_sel:[0,1,0]
	v_pk_fma_f32 v[98:99], v[122:123], v[42:43], v[40:41] op_sel_hi:[1,0,1]
	v_add_co_u32_e32 v40, vcc, s13, v80
	v_pk_fma_f32 v[44:45], v[118:119], v[44:45], v[92:93] op_sel:[0,1,0]
	v_pk_fma_f32 v[88:89], v[120:121], v[48:49], v[94:95] op_sel:[0,1,0]
	v_pk_fma_f32 v[48:49], v[118:119], v[48:49], v[96:97] op_sel:[0,1,0]
	v_addc_co_u32_e32 v41, vcc, 0, v81, vcc
	v_pk_fma_f32 v[84:85], v[124:125], v[42:43], v[84:85] op_sel_hi:[1,0,1]
	v_pk_fma_f32 v[86:87], v[124:125], v[46:47], v[86:87] op_sel_hi:[1,0,1]
	v_pk_fma_f32 v[44:45], v[122:123], v[46:47], v[44:45] op_sel_hi:[1,0,1]
	v_pk_fma_f32 v[88:89], v[124:125], v[50:51], v[88:89] op_sel_hi:[1,0,1]
	v_pk_fma_f32 v[48:49], v[122:123], v[50:51], v[48:49] op_sel_hi:[1,0,1]
	v_mov_b32_e32 v46, v11
	v_mov_b32_e32 v50, v43
	s_nop 0
	s_nop 0
	s_nop 0
	v_pk_fma_f32 v[52:53], v[118:119], v[52:53], v[100:101] op_sel:[0,1,0]
	v_pk_fma_f32 v[92:93], v[120:121], v[56:57], v[102:103] op_sel:[0,1,0]
	v_pk_fma_f32 v[56:57], v[118:119], v[56:57], v[104:105] op_sel:[0,1,0]
	v_pk_fma_f32 v[94:95], v[120:121], v[60:61], v[106:107] op_sel:[0,1,0]
	v_pk_fma_f32 v[60:61], v[118:119], v[60:61], v[108:109] op_sel:[0,1,0]
	v_pk_fma_f32 v[96:97], v[120:121], v[64:65], v[110:111] op_sel:[0,1,0]
	v_pk_fma_f32 v[64:65], v[118:119], v[64:65], v[112:113] op_sel:[0,1,0]
	v_pk_fma_f32 v[90:91], v[124:125], v[54:55], v[90:91] op_sel_hi:[1,0,1]
	v_pk_fma_f32 v[52:53], v[122:123], v[54:55], v[52:53] op_sel_hi:[1,0,1]
	v_pk_fma_f32 v[92:93], v[124:125], v[58:59], v[92:93] op_sel_hi:[1,0,1]
	v_pk_fma_f32 v[56:57], v[122:123], v[58:59], v[56:57] op_sel_hi:[1,0,1]
	v_pk_fma_f32 v[94:95], v[124:125], v[62:63], v[94:95] op_sel_hi:[1,0,1]
	v_pk_fma_f32 v[60:61], v[122:123], v[62:63], v[60:61] op_sel_hi:[1,0,1]
	v_pk_fma_f32 v[96:97], v[124:125], v[66:67], v[96:97] op_sel_hi:[1,0,1]
	v_pk_fma_f32 v[64:65], v[122:123], v[66:67], v[64:65] op_sel_hi:[1,0,1]
	v_pk_fma_f32 v[74:75], v[124:125], v[70:71], v[74:75] op_sel_hi:[1,0,1]
	v_pk_fma_f32 v[68:69], v[122:123], v[70:71], v[68:69] op_sel_hi:[1,0,1]
	v_mov_b32_e32 v54, v47
	v_mov_b32_e32 v58, v51
	v_mov_b32_e32 v62, v55
	v_mov_b32_e32 v66, v59
	v_mov_b32_e32 v70, v63
	v_mov_b32_e32 v100, v67
	v_mov_b32_e32 v102, v71
	s_mov_b32 s13, 0x1e000
	s_waitcnt vmcnt(4)
	v_mov_b32_e32 v8, v214
	v_mov_b32_e32 v9, v215
	v_mov_b32_e32 v10, v216
	v_mov_b32_e32 v11, v217
	v_pk_fma_f32 v[72:73], v[10:11], v[46:47], v[72:73] op_sel_hi:[1,0,1]
	v_pk_fma_f32 v[46:47], v[8:9], v[46:47], v[82:83] op_sel_hi:[1,0,1]
	v_pk_fma_f32 v[82:83], v[10:11], v[50:51], v[84:85] op_sel_hi:[1,0,1]
	v_pk_fma_f32 v[50:51], v[8:9], v[50:51], v[98:99] op_sel_hi:[1,0,1]
	v_pk_fma_f32 v[84:85], v[10:11], v[54:55], v[86:87] op_sel_hi:[1,0,1]
	v_pk_fma_f32 v[44:45], v[8:9], v[54:55], v[44:45] op_sel_hi:[1,0,1]
	v_pk_fma_f32 v[48:49], v[8:9], v[58:59], v[48:49] op_sel_hi:[1,0,1]
	v_pk_fma_f32 v[52:53], v[8:9], v[62:63], v[52:53] op_sel_hi:[1,0,1]
	v_pk_fma_f32 v[56:57], v[8:9], v[66:67], v[56:57] op_sel_hi:[1,0,1]
	v_pk_fma_f32 v[60:61], v[8:9], v[70:71], v[60:61] op_sel_hi:[1,0,1]
	v_pk_fma_f32 v[64:65], v[8:9], v[100:101], v[64:65] op_sel_hi:[1,0,1]
	v_pk_fma_f32 v[8:9], v[8:9], v[102:103], v[68:69] op_sel_hi:[1,0,1]
	v_pk_fma_f32 v[54:55], v[10:11], v[58:59], v[88:89] op_sel_hi:[1,0,1]
	v_pk_fma_f32 v[58:59], v[10:11], v[62:63], v[90:91] op_sel_hi:[1,0,1]
	v_pk_fma_f32 v[62:63], v[10:11], v[66:67], v[92:93] op_sel_hi:[1,0,1]
	v_pk_fma_f32 v[66:67], v[10:11], v[70:71], v[94:95] op_sel_hi:[1,0,1]
	v_pk_fma_f32 v[70:71], v[10:11], v[100:101], v[96:97] op_sel_hi:[1,0,1]
	v_pk_fma_f32 v[10:11], v[10:11], v[102:103], v[74:75] op_sel_hi:[1,0,1]
	s_waitcnt vmcnt(3)
; #define LAS __attribute__((address_space(3)))
; __device__ __forceinline__ void mod_item(const Params& p, LAS unsigned char* lds, int item, int tid, int wave, int lane) {
;     ...
;         for (int u = 0; u < 8; ++u) wv[u] = *(const f32x4*)(wp + (size_t)(k8 + u) * NMOD);
; #pragma unroll
;         for (int u = 0; u < 8; ++u)
; #pragma unroll
;             for (int r = 0; r < 9; ++r) { const float s = sv[r * 1024 + wave * 128 + k8 + u]; acc[r] += wv[u] * s; }
;     }
; #pragma unroll
;     for (int r = 0; r < 9; ++r) *(LAS f32x4*)(part + (wave * 9 + r) * 256 + 4 * lane) = acc[r];
;     __syncthreads();
;     float* mod = (float*)(p.ws + WS_MOD) + (size_t)l * 9 * NMOD;
;     for (int i = tid; i < 9 * 256; i += NTHR) { const int r = i >> 8, j = i & 255; float s = p.in[I_BMOD][l * NMOD + j0 + j];
	v_mov_b32_e32 v40, v224
	v_mov_b32_e32 v41, v225
	v_mov_b32_e32 v42, v226
	v_mov_b32_e32 v43, v227
	v_pk_fma_f32 v[74:75], v[42:43], v[24:25], v[84:85] op_sel_hi:[1,0,1]
	s_waitcnt lgkmcnt(0)
	v_pk_fma_f32 v[84:85], v[40:41], v[0:1], v[8:9] op_sel_hi:[1,0,1]
	v_add_co_u32_e32 v8, vcc, s13, v80
	s_mov_b32 s13, 0x24000
	s_nop 0
	v_addc_co_u32_e32 v9, vcc, 0, v81, vcc
	v_pk_fma_f32 v[68:69], v[42:43], v[16:17], v[72:73] op_sel_hi:[1,0,1]
	v_pk_fma_f32 v[72:73], v[42:43], v[20:21], v[82:83] op_sel_hi:[1,0,1]
	v_pk_fma_f32 v[82:83], v[42:43], v[0:1], v[10:11] op_sel_hi:[1,0,1]
	v_add_co_u32_e32 v10, vcc, s13, v80
	v_pk_fma_f32 v[46:47], v[40:41], v[16:17], v[46:47] op_sel_hi:[1,0,1]
	s_nop 0
	v_addc_co_u32_e32 v11, vcc, 0, v81, vcc
	v_pk_fma_f32 v[50:51], v[40:41], v[20:21], v[50:51] op_sel_hi:[1,0,1]
	v_pk_fma_f32 v[44:45], v[40:41], v[24:25], v[44:45] op_sel_hi:[1,0,1]
	v_pk_fma_f32 v[54:55], v[42:43], v[28:29], v[54:55] op_sel_hi:[1,0,1]
	v_pk_fma_f32 v[48:49], v[40:41], v[28:29], v[48:49] op_sel_hi:[1,0,1]
	v_pk_fma_f32 v[58:59], v[42:43], v[32:33], v[58:59] op_sel_hi:[1,0,1]
	v_pk_fma_f32 v[52:53], v[40:41], v[32:33], v[52:53] op_sel_hi:[1,0,1]
	v_pk_fma_f32 v[62:63], v[42:43], v[36:37], v[62:63] op_sel_hi:[1,0,1]
	v_pk_fma_f32 v[56:57], v[40:41], v[36:37], v[56:57] op_sel_hi:[1,0,1]
	v_pk_fma_f32 v[66:67], v[42:43], v[12:13], v[66:67] op_sel_hi:[1,0,1]
	v_pk_fma_f32 v[60:61], v[40:41], v[12:13], v[60:61] op_sel_hi:[1,0,1]
	v_pk_fma_f32 v[70:71], v[42:43], v[4:5], v[70:71] op_sel_hi:[1,0,1]
	v_pk_fma_f32 v[64:65], v[40:41], v[4:5], v[64:65] op_sel_hi:[1,0,1]
	s_nop 0
	s_nop 0
	s_nop 0
	s_mov_b32 s13, 0x2a000
	s_waitcnt vmcnt(2)
	v_mov_b32_e32 v40, v228
	v_mov_b32_e32 v41, v229
	v_mov_b32_e32 v42, v230
	v_mov_b32_e32 v43, v231
	v_pk_fma_f32 v[68:69], v[42:43], v[16:17], v[68:69] op_sel:[0,1,0]
	v_pk_fma_f32 v[46:47], v[40:41], v[16:17], v[46:47] op_sel:[0,1,0]
	v_pk_fma_f32 v[72:73], v[42:43], v[20:21], v[72:73] op_sel:[0,1,0]
	v_pk_fma_f32 v[50:51], v[40:41], v[20:21], v[50:51] op_sel:[0,1,0]
	v_pk_fma_f32 v[74:75], v[42:43], v[24:25], v[74:75] op_sel:[0,1,0]
	v_pk_fma_f32 v[44:45], v[40:41], v[24:25], v[44:45] op_sel:[0,1,0]
	v_pk_fma_f32 v[54:55], v[42:43], v[28:29], v[54:55] op_sel:[0,1,0]
	v_pk_fma_f32 v[48:49], v[40:41], v[28:29], v[48:49] op_sel:[0,1,0]
	v_pk_fma_f32 v[58:59], v[42:43], v[32:33], v[58:59] op_sel:[0,1,0]
	v_pk_fma_f32 v[52:53], v[40:41], v[32:33], v[52:53] op_sel:[0,1,0]
	v_pk_fma_f32 v[86:87], v[42:43], v[36:37], v[62:63] op_sel:[0,1,0]
	v_pk_fma_f32 v[56:57], v[40:41], v[36:37], v[56:57] op_sel:[0,1,0]
	v_pk_fma_f32 v[66:67], v[42:43], v[12:13], v[66:67] op_sel:[0,1,0]
	v_pk_fma_f32 v[12:13], v[40:41], v[12:13], v[60:61] op_sel:[0,1,0]
	v_pk_fma_f32 v[60:61], v[42:43], v[4:5], v[70:71] op_sel:[0,1,0]
	v_pk_fma_f32 v[62:63], v[40:41], v[4:5], v[64:65] op_sel:[0,1,0]
	v_pk_fma_f32 v[4:5], v[42:43], v[0:1], v[82:83] op_sel:[0,1,0]
	v_pk_fma_f32 v[0:1], v[40:41], v[0:1], v[84:85] op_sel:[0,1,0]
	s_waitcnt vmcnt(1)
	v_mov_b32_e32 v8, v232
	v_mov_b32_e32 v9, v233
	v_mov_b32_e32 v10, v234
	v_mov_b32_e32 v11, v235
	v_pk_fma_f32 v[16:17], v[10:11], v[18:19], v[68:69] op_sel_hi:[1,0,1]
	v_pk_fma_f32 v[20:21], v[8:9], v[18:19], v[46:47] op_sel_hi:[1,0,1]
	v_mov_b32_e32 v28, v19
	v_pk_fma_f32 v[18:19], v[10:11], v[22:23], v[72:73] op_sel_hi:[1,0,1]
	v_pk_fma_f32 v[24:25], v[8:9], v[22:23], v[50:51] op_sel_hi:[1,0,1]
	v_mov_b32_e32 v36, v23
	v_pk_fma_f32 v[22:23], v[10:11], v[26:27], v[74:75] op_sel_hi:[1,0,1]
	v_pk_fma_f32 v[32:33], v[8:9], v[26:27], v[44:45] op_sel_hi:[1,0,1]
	v_mov_b32_e32 v42, v27
	v_pk_fma_f32 v[26:27], v[10:11], v[30:31], v[54:55] op_sel_hi:[1,0,1]
	v_pk_fma_f32 v[40:41], v[8:9], v[30:31], v[48:49] op_sel_hi:[1,0,1]
	v_add_co_u32_e32 v30, vcc, s13, v80
	v_mov_b32_e32 v48, v31
	s_nop 0
	v_addc_co_u32_e32 v31, vcc, 0, v81, vcc
	v_pk_fma_f32 v[44:45], v[10:11], v[34:35], v[58:59] op_sel_hi:[1,0,1]
	v_pk_fma_f32 v[58:59], v[10:11], v[14:15], v[66:67] op_sel_hi:[1,0,1]
	v_pk_fma_f32 v[64:65], v[8:9], v[14:15], v[12:13] op_sel_hi:[1,0,1]
	v_mov_b32_e32 v68, v15
	s_nop 0
	v_pk_fma_f32 v[46:47], v[8:9], v[34:35], v[52:53] op_sel_hi:[1,0,1]
	v_mov_b32_e32 v54, v35
	v_pk_fma_f32 v[50:51], v[10:11], v[38:39], v[86:87] op_sel_hi:[1,0,1]
	v_pk_fma_f32 v[52:53], v[8:9], v[38:39], v[56:57] op_sel_hi:[1,0,1]
	v_mov_b32_e32 v56, v39
	v_pk_fma_f32 v[70:71], v[10:11], v[6:7], v[60:61] op_sel_hi:[1,0,1]
	v_pk_fma_f32 v[72:73], v[8:9], v[6:7], v[62:63] op_sel_hi:[1,0,1]
	v_mov_b32_e32 v74, v7
	v_mov_b32_e32 v82, v3
	v_pk_fma_f32 v[10:11], v[10:11], v[2:3], v[4:5] op_sel_hi:[1,0,1]
	v_pk_fma_f32 v[8:9], v[8:9], v[2:3], v[0:1] op_sel_hi:[1,0,1]
	v_lshl_add_u64 v[80:81], v[80:81], 0, s[14:15]
	s_waitcnt vmcnt(0)
	v_mov_b32_e32 v12, v236
	v_mov_b32_e32 v13, v237
	v_mov_b32_e32 v14, v238
	v_mov_b32_e32 v15, v239
	v_pk_fma_f32 v[2:3], v[14:15], v[28:29], v[16:17] op_sel_hi:[1,0,1]
	v_pk_fma_f32 v[0:1], v[12:13], v[28:29], v[20:21] op_sel_hi:[1,0,1]
	v_pk_fma_f32 v[6:7], v[14:15], v[36:37], v[18:19] op_sel_hi:[1,0,1]
	v_pk_fma_f32 v[4:5], v[12:13], v[36:37], v[24:25] op_sel_hi:[1,0,1]
	v_pk_fma_f32 v[30:31], v[14:15], v[42:43], v[22:23] op_sel_hi:[1,0,1]
	v_pk_fma_f32 v[28:29], v[12:13], v[42:43], v[32:33] op_sel_hi:[1,0,1]
	v_pk_fma_f32 v[34:35], v[14:15], v[48:49], v[26:27] op_sel_hi:[1,0,1]
	v_pk_fma_f32 v[32:33], v[12:13], v[48:49], v[40:41] op_sel_hi:[1,0,1]
	v_pk_fma_f32 v[38:39], v[14:15], v[54:55], v[44:45] op_sel_hi:[1,0,1]
	v_pk_fma_f32 v[36:37], v[12:13], v[54:55], v[46:47] op_sel_hi:[1,0,1]
	v_pk_fma_f32 v[62:63], v[14:15], v[56:57], v[50:51] op_sel_hi:[1,0,1]
	v_pk_fma_f32 v[60:61], v[12:13], v[56:57], v[52:53] op_sel_hi:[1,0,1]
	v_pk_fma_f32 v[66:67], v[14:15], v[68:69], v[58:59] op_sel_hi:[1,0,1]
	v_pk_fma_f32 v[64:65], v[12:13], v[68:69], v[64:65] op_sel_hi:[1,0,1]
	v_pk_fma_f32 v[70:71], v[14:15], v[74:75], v[70:71] op_sel_hi:[1,0,1]
	v_pk_fma_f32 v[68:69], v[12:13], v[74:75], v[72:73] op_sel_hi:[1,0,1]
	v_pk_fma_f32 v[74:75], v[14:15], v[82:83], v[10:11] op_sel_hi:[1,0,1]
	v_pk_fma_f32 v[72:73], v[12:13], v[82:83], v[8:9] op_sel_hi:[1,0,1]
	s_cbranch_scc0 .LBB0_374
	ds_write_b128 v117, v[0:3] offset:36864
	ds_write_b128 v117, v[4:7] offset:37888
	ds_write_b128 v117, v[28:31] offset:38912
	ds_write_b128 v117, v[32:35] offset:39936
	ds_write_b128 v117, v[36:39] offset:40960
	ds_write_b128 v117, v[60:63] offset:41984
	ds_write_b128 v117, v[64:67] offset:43008
	ds_write_b128 v117, v[68:71] offset:44032
	ds_write_b128 v117, v[72:75] offset:45056
	s_waitcnt lgkmcnt(0)
	s_barrier
	s_and_saveexec_b64 s[12:13], s[6:7]
	s_cbranch_execz .LBB0_369
	s_mul_i32 s14, s18, 0x36000
	s_mul_hi_i32 s11, s18, 0x36000
	s_add_u32 s14, s73, s14
	s_addc_u32 s15, s57, s11
	s_mul_i32 s11, s18, 0x1800
	s_add_i32 s11, s11, s10
	v_or_b32_e32 v0, s11, v114
	v_ashrrev_i32_e32 v1, 31, v0
	v_lshl_add_u64 v[0:1], v[0:1], 2, s[8:9]
	v_or_b32_e32 v2, s10, v114
	s_mov_b64 s[10:11], 0
	v_mov_b32_e32 v3, v166
